# down GEMM sample rows split K 16 ways (was 8) so 128 workgroups carry a quarter-tile unit; LN2 sums 16 slabs and gives the slab-heavy sample rows to waves that otherwise have one row fewer
# speedup vs baseline: 1.0046x; 1.0046x over previous
.LBB0_1723:
	s_cmp_lt_i32 s56, 10
	s_cselect_b64 s[4:5], -1, 0
	s_and_b64 s[4:5], s[4:5], s[0:1]
	s_andn2_b64 vcc, exec, s[4:5]
	s_cbranch_vccnz .LBB0_1765
	s_cmpk_gt_i32 s2, 0xff
	v_readfirstlane_b32 s14, v166
	s_cbranch_scc0 .LBB0_1730
	s_and_b32 s0, s2, 0x7fffff80
	s_mov_b64 s[6:7], 0
	s_cmpk_eq_i32 s0, 0x100
	s_mov_b64 s[0:1], 0
	s_cbranch_scc0 .LBB0_1727
	s_lshl_b32 s0, s2, 6
	s_and_b32 s28, s2, 7
	s_and_b32 s55, s0, 0x1e00
	s_mov_b64 s[0:1], -1

.LBB0_1731:
	s_mov_b32 s58, 1
	s_mov_b32 s59, 8
	s_mov_b32 s30, 32
	s_and_b64 vcc, exec, s[0:1]
	s_cbranch_vccnz .LBB0_1735
	s_branch .LBB0_1765

.LBB0_1740:
	s_add_i32 s52, s52, 1
	s_mul_i32 s0, s52, s47
	s_mul_hi_u32 s1, s52, s33
	s_add_i32 s1, s1, s0
	s_mul_i32 s0, s52, s33
	s_add_u32 s0, s0, s2
	s_addc_u32 s1, s1, s48
	v_cmp_gt_i64_e32 vcc, s[0:1], v[146:147]
	s_mov_b64 s[26:27], -1
	s_cbranch_vccz .LBB0_1743
	s_add_i32 s1, s0, 0xffffff00
	s_mov_b64 s[26:27], 0
	s_cmp_gt_i32 s1, 127
	s_mov_b64 s[24:25], 0
	s_cbranch_scc1 .LBB0_1743
	s_ashr_i32 s18, s1, 31
	s_lshr_b32 s18, s18, 29
	s_add_i32 s18, s1, s18
	s_and_b32 s19, s18, -8
	s_sub_i32 s20, s1, s19
	s_lshl_b32 s1, s18, 6
	s_and_b32 s18, s1, 0xfffffe00
	s_mov_b32 s54, 1
	s_mov_b32 s53, 8
	s_mov_b32 s22, 32
	s_mov_b64 s[24:25], -1

.LBB0_1757:
	s_cmp_eq_u32 s58, 0
	s_cbranch_scc1 .LBB0_1763
	s_ashr_i32 s19, s55, 31
	s_lshr_b32 s19, s19, 23
	s_add_i32 s19, s55, s19
	s_ashr_i32 s34, s19, 9
	s_ashr_i32 s35, s34, 31
	s_lshl_b64 s[34:35], s[34:35], 20
	v_lshl_add_u64 v[148:149], v[140:141], 0, s[34:35]
	s_lshl_b32 s34, s28, 8
	s_ashr_i32 s35, s34, 31
	v_lshl_add_u64 v[148:149], s[34:35], 2, v[148:149]
	v_lshl_add_u64 v[148:149], v[148:149], 0, s[6:7]
	v_lshl_add_u64 v[148:149], v[148:149], 0, v[136:137]
	v_add_co_u32_e32 v150, vcc, s51, v148
	global_store_dwordx4 v[148:149], v[124:127], off
	global_store_dwordx4 v[148:149], v[120:123], off offset:16
	global_store_dwordx4 v[148:149], v[116:119], off offset:512
	global_store_dwordx4 v[148:149], v[112:115], off offset:528
	v_addc_co_u32_e32 v151, vcc, 0, v149, vcc
	global_store_dwordx4 v[150:151], v[108:111], off
	global_store_dwordx4 v[150:151], v[104:107], off offset:16
	global_store_dwordx4 v[150:151], v[100:103], off offset:512
	global_store_dwordx4 v[150:151], v[96:99], off offset:528
	v_add_co_u32_e32 v150, vcc, 0x40000, v148
	s_nop 1
	v_addc_co_u32_e32 v151, vcc, 0, v149, vcc
	v_add_co_u32_e32 v148, vcc, 0x60000, v148
	global_store_dwordx4 v[150:151], v[92:95], off
	global_store_dwordx4 v[150:151], v[88:91], off offset:16
	global_store_dwordx4 v[150:151], v[84:87], off offset:512
	global_store_dwordx4 v[150:151], v[80:83], off offset:528
	v_addc_co_u32_e32 v149, vcc, 0, v149, vcc
	global_store_dwordx4 v[148:149], v[76:79], off
	global_store_dwordx4 v[148:149], v[72:75], off offset:16
	global_store_dwordx4 v[148:149], v[68:71], off offset:512
	global_store_dwordx4 v[148:149], v[64:67], off offset:528
	s_cbranch_execnz .LBB0_1760

.LBB0_1824:
	v_add_u32_e32 v1, 0xffffff80, v90
	v_cmp_gt_i32_e32 vcc, s27, v90
	v_add_u32_e32 v0, 0x1f80, v90
	s_nop 0
	v_cndmask_b32_e32 v1, v90, v1, vcc
	v_cmp_gt_u32_e32 vcc, s26, v1
	s_nop 1
	v_cndmask_b32_e32 v22, v1, v0, vcc
	v_cmp_gt_i32_e32 vcc, s26, v90
	s_nop 1
	v_cndmask_b32_e32 v22, v22, v90, vcc
	v_cmp_gt_i32_e32 vcc, s27, v22
	s_and_saveexec_b64 s[22:23], vcc
	s_cbranch_execz .LBB0_1823
	v_cmp_lt_i32_e32 vcc, s28, v22
	s_and_saveexec_b64 s[24:25], vcc
	s_xor_b64 s[24:25], exec, s[24:25]
	s_cbranch_execz .LBB0_1827
	v_add_u32_e32 v0, 0xffffe000, v22
	v_mov_b32_e32 v1, v29
	v_lshlrev_b64 v[0:1], 13, v[0:1]
	v_lshl_add_u64 v[2:3], s[0:1], 0, v[0:1]
	v_lshl_add_u64 v[16:17], v[2:3], 0, v[28:29]
	v_mov_b32_e32 v57, v29
	v_mov_b32_e32 v59, v29
	global_load_dwordx4 v[4:7], v[16:17], off
	global_load_dwordx4 v[8:11], v[16:17], off offset:1024
	global_load_dwordx4 v[12:15], v[16:17], off offset:2048
	global_load_dwordx4 v[24:27], v[16:17], off offset:3072
	v_lshl_add_u64 v[16:17], v[2:3], 0, v[56:57]
	v_lshl_add_u64 v[18:19], v[2:3], 0, v[58:59]
	global_load_dwordx4 v[64:67], v[16:17], off
	global_load_dwordx4 v[68:71], v[18:19], off
	v_mov_b32_e32 v61, v29
	v_lshl_add_u64 v[18:19], s[2:3], 0, v[0:1]
	v_lshl_add_u64 v[16:17], v[2:3], 0, v[60:61]
	v_mov_b32_e32 v63, v29
	v_lshl_add_u64 v[0:1], v[18:19], 0, v[28:29]
	v_lshl_add_u64 v[2:3], v[2:3], 0, v[62:63]
	global_load_dwordx4 v[72:75], v[16:17], off
	global_load_dwordx4 v[76:79], v[2:3], off
	global_load_dwordx4 v[80:83], v[0:1], off
	global_load_dwordx4 v[84:87], v[0:1], off offset:1024
	global_load_dwordx4 v[94:97], v[0:1], off offset:2048
	global_load_dwordx4 v[98:101], v[0:1], off offset:3072
	v_lshl_add_u64 v[0:1], v[18:19], 0, v[56:57]
	v_lshl_add_u64 v[2:3], v[18:19], 0, v[58:59]
	global_load_dwordx4 v[102:105], v[0:1], off
	global_load_dwordx4 v[106:109], v[2:3], off
	v_lshl_add_u64 v[0:1], v[18:19], 0, v[60:61]
	v_lshl_add_u64 v[2:3], v[18:19], 0, v[62:63]
	global_load_dwordx4 v[110:113], v[0:1], off
	global_load_dwordx4 v[114:117], v[2:3], off
	v_lshl_add_u64 v[0:1], v[18:19], 0, s[8:9]
	v_lshl_add_u64 v[2:3], v[0:1], 0, v[28:29]
	v_mov_b32_e32 v51, v29
	v_mov_b32_e32 v53, v29
	v_lshl_add_u64 v[16:17], v[0:1], 0, v[50:51]
	global_load_dwordx4 v[118:121], v[2:3], off
	global_load_dwordx4 v[122:125], v[16:17], off
	v_lshl_add_u64 v[2:3], v[0:1], 0, v[52:53]
	v_mov_b32_e32 v55, v29
	v_lshl_add_u64 v[16:17], v[0:1], 0, v[54:55]
	global_load_dwordx4 v[126:129], v[2:3], off
	global_load_dwordx4 v[130:133], v[16:17], off
	v_lshl_add_u64 v[2:3], v[0:1], 0, v[56:57]
	v_lshl_add_u64 v[16:17], v[0:1], 0, v[58:59]
	global_load_dwordx4 v[134:137], v[2:3], off
	global_load_dwordx4 v[138:141], v[16:17], off
	v_lshl_add_u64 v[2:3], v[0:1], 0, v[60:61]
	v_lshl_add_u64 v[0:1], v[0:1], 0, v[62:63]
	global_load_dwordx4 v[142:145], v[2:3], off
	global_load_dwordx4 v[146:149], v[0:1], off
	v_lshl_add_u64 v[0:1], v[18:19], 0, s[10:11]
	v_lshl_add_u64 v[2:3], v[0:1], 0, v[28:29]
	global_load_dwordx4 v[150:153], v[2:3], off
	v_lshl_add_u64 v[2:3], v[0:1], 0, v[50:51]
	global_load_dwordx4 v[154:157], v[2:3], off
	v_lshl_add_u64 v[2:3], v[0:1], 0, v[52:53]
	global_load_dwordx4 v[158:161], v[2:3], off
	v_lshl_add_u64 v[2:3], v[0:1], 0, v[54:55]
	global_load_dwordx4 v[162:165], v[2:3], off
	v_lshl_add_u64 v[2:3], v[0:1], 0, v[56:57]
	global_load_dwordx4 v[166:169], v[2:3], off
	v_lshl_add_u64 v[2:3], v[0:1], 0, v[58:59]
	global_load_dwordx4 v[170:173], v[2:3], off
	v_lshl_add_u64 v[2:3], v[0:1], 0, v[60:61]
	v_lshl_add_u64 v[0:1], v[0:1], 0, v[62:63]
	global_load_dwordx4 v[174:177], v[2:3], off
	v_lshl_add_u64 v[198:199], v[18:19], 0, s[18:19]
	global_load_dwordx4 v[0:3], v[0:1], off
	v_lshl_add_u64 v[178:179], v[198:199], 0, v[50:51]
	v_lshl_add_u64 v[182:183], v[198:199], 0, v[52:53]
	v_lshl_add_u64 v[186:187], v[198:199], 0, v[54:55]
	v_lshl_add_u64 v[190:191], v[198:199], 0, v[56:57]
	v_lshl_add_u64 v[194:195], v[198:199], 0, v[58:59]
	v_lshl_add_u64 v[200:201], v[198:199], 0, v[60:61]
	v_lshl_add_u64 v[202:203], v[198:199], 0, v[62:63]
	s_waitcnt vmcnt(23)
	v_pk_fma_f32 v[4:5], v[4:5], s[6:7], v[80:81] op_sel_hi:[1,0,1]
	v_pk_fma_f32 v[6:7], v[6:7], s[6:7], v[82:83] op_sel_hi:[1,0,1]
	s_waitcnt vmcnt(22)
	v_pk_fma_f32 v[10:11], v[10:11], s[6:7], v[86:87] op_sel_hi:[1,0,1]
	s_waitcnt vmcnt(20)
	v_pk_fma_f32 v[16:17], v[26:27], s[6:7], v[100:101] op_sel_hi:[1,0,1]
	v_pk_fma_f32 v[20:21], v[24:25], s[6:7], v[98:99] op_sel_hi:[1,0,1]
	s_waitcnt vmcnt(19)
	v_pk_fma_f32 v[24:25], v[66:67], s[6:7], v[104:105] op_sel_hi:[1,0,1]
	v_pk_fma_f32 v[26:27], v[64:65], s[6:7], v[102:103] op_sel_hi:[1,0,1]
	s_waitcnt vmcnt(18)
	v_pk_fma_f32 v[64:65], v[70:71], s[6:7], v[108:109] op_sel_hi:[1,0,1]
	v_pk_fma_f32 v[66:67], v[68:69], s[6:7], v[106:107] op_sel_hi:[1,0,1]
	s_waitcnt vmcnt(17)
	v_pk_fma_f32 v[68:69], v[74:75], s[6:7], v[112:113] op_sel_hi:[1,0,1]
	v_pk_fma_f32 v[70:71], v[72:73], s[6:7], v[110:111] op_sel_hi:[1,0,1]
	s_waitcnt vmcnt(16)
	v_pk_fma_f32 v[72:73], v[78:79], s[6:7], v[116:117] op_sel_hi:[1,0,1]
	v_pk_fma_f32 v[8:9], v[8:9], s[6:7], v[84:85] op_sel_hi:[1,0,1]
	v_pk_fma_f32 v[14:15], v[14:15], s[6:7], v[96:97] op_sel_hi:[1,0,1]
	v_pk_fma_f32 v[12:13], v[12:13], s[6:7], v[94:95] op_sel_hi:[1,0,1]
	v_pk_fma_f32 v[74:75], v[76:77], s[6:7], v[114:115] op_sel_hi:[1,0,1]
	s_waitcnt vmcnt(15)
	v_pk_add_f32 v[4:5], v[4:5], v[118:119]
	v_lshl_add_u64 v[102:103], v[18:19], 0, s[12:13]
	v_pk_add_f32 v[6:7], v[6:7], v[120:121]
	s_waitcnt vmcnt(12)
	v_pk_add_f32 v[76:77], v[20:21], v[130:131]
	v_pk_add_f32 v[10:11], v[10:11], v[124:125]
	s_waitcnt vmcnt(11)
	v_pk_add_f32 v[78:79], v[24:25], v[136:137]
	v_pk_add_f32 v[80:81], v[26:27], v[134:135]
	s_waitcnt vmcnt(10)
	v_pk_add_f32 v[82:83], v[64:65], v[140:141]
	v_pk_add_f32 v[84:85], v[66:67], v[138:139]
	s_waitcnt vmcnt(9)
	v_pk_add_f32 v[86:87], v[68:69], v[144:145]
	v_pk_add_f32 v[88:89], v[70:71], v[142:143]
	s_waitcnt vmcnt(8)
	v_pk_add_f32 v[94:95], v[72:73], v[148:149]
	v_lshl_add_u64 v[134:135], v[18:19], 0, s[14:15]
	v_pk_add_f32 v[8:9], v[8:9], v[122:123]
	v_pk_add_f32 v[14:15], v[14:15], v[128:129]
	v_pk_add_f32 v[12:13], v[12:13], v[126:127]
	v_pk_add_f32 v[16:17], v[16:17], v[132:133]
	v_pk_add_f32 v[20:21], v[74:75], v[146:147]
	s_waitcnt vmcnt(7)
	v_pk_add_f32 v[26:27], v[4:5], v[150:151]
	s_waitcnt vmcnt(4)
	v_pk_add_f32 v[74:75], v[76:77], v[162:163]
	s_waitcnt vmcnt(3)
	v_pk_add_f32 v[76:77], v[78:79], v[168:169]
	v_pk_add_f32 v[78:79], v[80:81], v[166:167]
	s_waitcnt vmcnt(2)
	v_pk_add_f32 v[80:81], v[82:83], v[172:173]
	v_pk_add_f32 v[82:83], v[84:85], v[170:171]
	v_lshl_add_u64 v[4:5], v[102:103], 0, v[50:51]
	s_waitcnt vmcnt(1)
	v_pk_add_f32 v[84:85], v[86:87], v[176:177]
	v_pk_add_f32 v[86:87], v[88:89], v[174:175]
	s_waitcnt vmcnt(0)
	v_pk_add_f32 v[88:89], v[94:95], v[2:3]
	v_lshl_add_u64 v[2:3], v[102:103], 0, v[28:29]
	v_lshl_add_u64 v[94:95], v[102:103], 0, v[52:53]
	v_lshl_add_u64 v[96:97], v[102:103], 0, v[54:55]
	v_lshl_add_u64 v[104:105], v[102:103], 0, v[56:57]
	v_lshl_add_u64 v[106:107], v[102:103], 0, v[58:59]
	v_lshl_add_u64 v[110:111], v[102:103], 0, v[60:61]
	v_lshl_add_u64 v[112:113], v[102:103], 0, v[62:63]
	v_lshl_add_u64 v[118:119], v[134:135], 0, v[28:29]
	v_pk_add_f32 v[24:25], v[6:7], v[152:153]
	v_pk_add_f32 v[64:65], v[10:11], v[156:157]
	v_pk_add_f32 v[66:67], v[8:9], v[154:155]
	v_pk_add_f32 v[68:69], v[14:15], v[160:161]
	v_pk_add_f32 v[70:71], v[12:13], v[158:159]
	v_pk_add_f32 v[72:73], v[16:17], v[164:165]
	global_load_dwordx4 v[6:9], v[2:3], off
	s_nop 0
	global_load_dwordx4 v[2:5], v[4:5], off
	s_nop 0
	global_load_dwordx4 v[14:17], v[94:95], off
	global_load_dwordx4 v[10:13], v[96:97], off
	s_nop 0
	global_load_dwordx4 v[94:97], v[104:105], off
	global_load_dwordx4 v[98:101], v[106:107], off
	s_nop 0
	global_load_dwordx4 v[102:105], v[110:111], off
	global_load_dwordx4 v[106:109], v[112:113], off
	v_lshl_add_u64 v[120:121], v[134:135], 0, v[50:51]
	global_load_dwordx4 v[110:113], v[118:119], off
	global_load_dwordx4 v[114:117], v[120:121], off
	v_lshl_add_u64 v[118:119], v[134:135], 0, v[52:53]
	v_lshl_add_u64 v[122:123], v[134:135], 0, v[54:55]
	v_lshl_add_u64 v[126:127], v[134:135], 0, v[56:57]
	v_lshl_add_u64 v[130:131], v[134:135], 0, v[58:59]
	v_lshl_add_u64 v[166:167], v[18:19], 0, s[16:17]
	global_load_dwordx4 v[118:121], v[118:119], off
	s_nop 0
	global_load_dwordx4 v[122:125], v[122:123], off
	s_nop 0
	global_load_dwordx4 v[126:129], v[126:127], off
	s_nop 0
	global_load_dwordx4 v[130:133], v[130:131], off
	v_lshl_add_u64 v[136:137], v[134:135], 0, v[60:61]
	v_lshl_add_u64 v[138:139], v[134:135], 0, v[62:63]
	v_lshl_add_u64 v[142:143], v[166:167], 0, v[28:29]
	v_lshl_add_u64 v[146:147], v[166:167], 0, v[50:51]
	v_lshl_add_u64 v[150:151], v[166:167], 0, v[52:53]
	v_lshl_add_u64 v[154:155], v[166:167], 0, v[54:55]
	v_lshl_add_u64 v[158:159], v[166:167], 0, v[56:57]
	v_lshl_add_u64 v[162:163], v[166:167], 0, v[58:59]
	global_load_dwordx4 v[134:137], v[136:137], off
	s_nop 0
	global_load_dwordx4 v[138:141], v[138:139], off
	s_nop 0
	global_load_dwordx4 v[142:145], v[142:143], off
	s_nop 0
	global_load_dwordx4 v[146:149], v[146:147], off
	s_nop 0
	global_load_dwordx4 v[150:153], v[150:151], off
	s_nop 0
	global_load_dwordx4 v[154:157], v[154:155], off
	s_nop 0
	global_load_dwordx4 v[158:161], v[158:159], off
	s_nop 0
	global_load_dwordx4 v[162:165], v[162:163], off
	v_lshl_add_u64 v[168:169], v[166:167], 0, v[60:61]
	v_lshl_add_u64 v[170:171], v[166:167], 0, v[62:63]
	v_lshl_add_u64 v[174:175], v[198:199], 0, v[28:29]
	v_lshl_add_u64 v[18:19], v[18:19], 0, s[20:21]
	global_load_dwordx4 v[166:169], v[168:169], off
	s_nop 0
	global_load_dwordx4 v[170:173], v[170:171], off
	s_nop 0
	global_load_dwordx4 v[174:177], v[174:175], off
	s_nop 0
	global_load_dwordx4 v[178:181], v[178:179], off
	s_nop 0
	global_load_dwordx4 v[182:185], v[182:183], off
	s_nop 0
	global_load_dwordx4 v[186:189], v[186:187], off
	s_nop 0
	global_load_dwordx4 v[190:193], v[190:191], off
	s_nop 0
	global_load_dwordx4 v[194:197], v[194:195], off
	v_lshl_add_u64 v[206:207], v[18:19], 0, v[28:29]
	v_lshl_add_u64 v[210:211], v[18:19], 0, v[50:51]
	v_lshl_add_u64 v[214:215], v[18:19], 0, v[52:53]
	v_lshl_add_u64 v[218:219], v[18:19], 0, v[54:55]
	v_lshl_add_u64 v[222:223], v[18:19], 0, v[56:57]
	v_lshl_add_u64 v[226:227], v[18:19], 0, v[58:59]
	global_load_dwordx4 v[198:201], v[200:201], off
	s_nop 0
	global_load_dwordx4 v[202:205], v[202:203], off
	v_lshl_add_u64 v[230:231], v[18:19], 0, v[60:61]
	global_load_dwordx4 v[206:209], v[206:207], off
	v_lshl_add_u64 v[18:19], v[18:19], 0, v[62:63]
	global_load_dwordx4 v[210:213], v[210:211], off
	v_pk_add_f32 v[0:1], v[20:21], v[0:1]
	global_load_dwordx4 v[214:217], v[214:215], off
	s_waitcnt vmcnt(34)
	v_pk_add_f32 v[8:9], v[24:25], v[8:9]
	global_load_dwordx4 v[218:221], v[218:219], off
	v_pk_add_f32 v[6:7], v[26:27], v[6:7]
	global_load_dwordx4 v[222:225], v[222:223], off
	s_waitcnt vmcnt(35)
	v_pk_add_f32 v[4:5], v[64:65], v[4:5]
	global_load_dwordx4 v[226:229], v[226:227], off
	v_pk_add_f32 v[2:3], v[66:67], v[2:3]
	global_load_dwordx4 v[230:233], v[230:231], off
	s_waitcnt vmcnt(36)
	v_pk_add_f32 v[16:17], v[68:69], v[16:17]
	global_load_dwordx4 v[234:237], v[18:19], off
	v_pk_add_f32 v[14:15], v[70:71], v[14:15]
	s_waitcnt vmcnt(36)
	v_pk_add_f32 v[12:13], v[72:73], v[12:13]
	v_pk_add_f32 v[10:11], v[74:75], v[10:11]
	s_waitcnt vmcnt(35)
	v_pk_add_f32 v[18:19], v[76:77], v[96:97]
	v_pk_add_f32 v[20:21], v[78:79], v[94:95]
	s_waitcnt vmcnt(34)
	v_pk_add_f32 v[24:25], v[80:81], v[100:101]
	v_pk_add_f32 v[26:27], v[82:83], v[98:99]
	s_waitcnt vmcnt(33)
	v_pk_add_f32 v[64:65], v[84:85], v[104:105]
	v_pk_add_f32 v[66:67], v[86:87], v[102:103]
	s_waitcnt vmcnt(32)
	v_pk_add_f32 v[68:69], v[88:89], v[108:109]
	v_pk_add_f32 v[0:1], v[0:1], v[106:107]
	s_waitcnt vmcnt(31)
	v_pk_add_f32 v[8:9], v[8:9], v[112:113]
	v_pk_add_f32 v[6:7], v[6:7], v[110:111]
	s_waitcnt vmcnt(30)
	v_pk_add_f32 v[4:5], v[4:5], v[116:117]
	v_pk_add_f32 v[2:3], v[2:3], v[114:115]
	s_waitcnt vmcnt(29)
	v_pk_add_f32 v[16:17], v[16:17], v[120:121]
	v_pk_add_f32 v[14:15], v[14:15], v[118:119]
	s_waitcnt vmcnt(28)
	v_pk_add_f32 v[12:13], v[12:13], v[124:125]
	v_pk_add_f32 v[10:11], v[10:11], v[122:123]
	s_waitcnt vmcnt(27)
	v_pk_add_f32 v[18:19], v[18:19], v[128:129]
	v_pk_add_f32 v[20:21], v[20:21], v[126:127]
	s_waitcnt vmcnt(26)
	v_pk_add_f32 v[24:25], v[24:25], v[132:133]
	v_pk_add_f32 v[26:27], v[26:27], v[130:131]
	s_waitcnt vmcnt(25)
	v_pk_add_f32 v[64:65], v[64:65], v[136:137]
	v_pk_add_f32 v[66:67], v[66:67], v[134:135]
	s_waitcnt vmcnt(24)
	v_pk_add_f32 v[68:69], v[68:69], v[140:141]
	v_pk_add_f32 v[0:1], v[0:1], v[138:139]
	s_waitcnt vmcnt(23)
	v_pk_add_f32 v[8:9], v[8:9], v[144:145]
	v_pk_add_f32 v[6:7], v[6:7], v[142:143]
	s_waitcnt vmcnt(22)
	v_pk_add_f32 v[4:5], v[4:5], v[148:149]
	v_pk_add_f32 v[2:3], v[2:3], v[146:147]
	s_waitcnt vmcnt(21)
	v_pk_add_f32 v[16:17], v[16:17], v[152:153]
	v_pk_add_f32 v[14:15], v[14:15], v[150:151]
	s_waitcnt vmcnt(20)
	v_pk_add_f32 v[12:13], v[12:13], v[156:157]
	v_pk_add_f32 v[10:11], v[10:11], v[154:155]
	s_waitcnt vmcnt(19)
	v_pk_add_f32 v[18:19], v[18:19], v[160:161]
	v_pk_add_f32 v[20:21], v[20:21], v[158:159]
	s_waitcnt vmcnt(18)
	v_pk_add_f32 v[24:25], v[24:25], v[164:165]
	v_pk_add_f32 v[26:27], v[26:27], v[162:163]
	s_waitcnt vmcnt(17)
	v_pk_add_f32 v[64:65], v[64:65], v[168:169]
	v_pk_add_f32 v[66:67], v[66:67], v[166:167]
	s_waitcnt vmcnt(16)
	v_pk_add_f32 v[68:69], v[68:69], v[172:173]
	v_pk_add_f32 v[0:1], v[0:1], v[170:171]
	s_waitcnt vmcnt(15)
	v_pk_add_f32 v[8:9], v[8:9], v[176:177]
	v_pk_add_f32 v[6:7], v[6:7], v[174:175]
	s_waitcnt vmcnt(14)
	v_pk_add_f32 v[4:5], v[4:5], v[180:181]
	v_pk_add_f32 v[2:3], v[2:3], v[178:179]
	s_waitcnt vmcnt(13)
	v_pk_add_f32 v[16:17], v[16:17], v[184:185]
	v_pk_add_f32 v[14:15], v[14:15], v[182:183]
	s_waitcnt vmcnt(12)
	v_pk_add_f32 v[12:13], v[12:13], v[188:189]
	v_pk_add_f32 v[10:11], v[10:11], v[186:187]
	s_waitcnt vmcnt(11)
	v_pk_add_f32 v[74:75], v[18:19], v[192:193]
	v_pk_add_f32 v[76:77], v[20:21], v[190:191]
	s_waitcnt vmcnt(10)
	v_pk_add_f32 v[24:25], v[24:25], v[196:197]
	v_pk_add_f32 v[26:27], v[26:27], v[194:195]
	s_waitcnt vmcnt(9)
	v_pk_add_f32 v[64:65], v[64:65], v[200:201]
	v_pk_add_f32 v[66:67], v[66:67], v[198:199]
	s_waitcnt vmcnt(8)
	v_pk_add_f32 v[68:69], v[68:69], v[204:205]
	v_pk_add_f32 v[78:79], v[0:1], v[202:203]
	s_waitcnt vmcnt(7)
	v_pk_add_f32 v[80:81], v[8:9], v[208:209]
	v_pk_add_f32 v[82:83], v[6:7], v[206:207]
	s_waitcnt vmcnt(6)
	v_pk_add_f32 v[70:71], v[4:5], v[212:213]
	v_pk_add_f32 v[72:73], v[2:3], v[210:211]
	s_waitcnt vmcnt(5)
	v_pk_add_f32 v[20:21], v[16:17], v[216:217]
	v_pk_add_f32 v[84:85], v[14:15], v[214:215]
	s_waitcnt vmcnt(4)
	v_pk_add_f32 v[18:19], v[12:13], v[220:221]
	v_pk_add_f32 v[16:17], v[10:11], v[218:219]
	s_waitcnt vmcnt(3)
	v_pk_add_f32 v[14:15], v[74:75], v[224:225]
	v_pk_add_f32 v[12:13], v[76:77], v[222:223]
	s_waitcnt vmcnt(2)
	v_pk_add_f32 v[8:9], v[24:25], v[228:229]
	v_pk_add_f32 v[10:11], v[26:27], v[226:227]
	s_waitcnt vmcnt(1)
	v_pk_add_f32 v[2:3], v[64:65], v[232:233]
	v_pk_add_f32 v[0:1], v[66:67], v[230:231]
	s_waitcnt vmcnt(0)
	v_pk_add_f32 v[6:7], v[68:69], v[236:237]
	v_pk_add_f32 v[4:5], v[78:79], v[234:235]
	v_add_u32_e32 v86, 0xffffe000, v22
	v_mov_b32_e32 v87, 0
	v_lshlrev_b64 v[86:87], 13, v[86:87]
	v_lshl_add_u64 v[86:87], s[2:3], 0, v[86:87]
	v_lshl_add_u64 v[86:87], v[86:87], 0, v[28:29]
	s_mov_b32 s40, 0x800000
	s_mov_b32 s41, 0
	v_lshl_add_u64 v[88:89], v[86:87], 0, s[40:41]
	s_mov_b32 s40, 0x801000
	v_lshl_add_u64 v[94:95], v[86:87], 0, s[40:41]
	global_load_dwordx4 v[96:99], v[88:89], off
	global_load_dwordx4 v[100:103], v[88:89], off offset:1024
	global_load_dwordx4 v[104:107], v[88:89], off offset:2048
	global_load_dwordx4 v[108:111], v[88:89], off offset:3072
	global_load_dwordx4 v[112:115], v[94:95], off
	global_load_dwordx4 v[116:119], v[94:95], off offset:1024
	global_load_dwordx4 v[120:123], v[94:95], off offset:2048
	global_load_dwordx4 v[124:127], v[94:95], off offset:3072
	s_mov_b32 s40, 0x900000
	s_mov_b32 s41, 0
	v_lshl_add_u64 v[88:89], v[86:87], 0, s[40:41]
	s_mov_b32 s40, 0x901000
	v_lshl_add_u64 v[94:95], v[86:87], 0, s[40:41]
	global_load_dwordx4 v[128:131], v[88:89], off
	global_load_dwordx4 v[132:135], v[88:89], off offset:1024
	global_load_dwordx4 v[136:139], v[88:89], off offset:2048
	global_load_dwordx4 v[140:143], v[88:89], off offset:3072
	global_load_dwordx4 v[144:147], v[94:95], off
	global_load_dwordx4 v[148:151], v[94:95], off offset:1024
	global_load_dwordx4 v[152:155], v[94:95], off offset:2048
	global_load_dwordx4 v[156:159], v[94:95], off offset:3072
	s_mov_b32 s40, 0xa00000
	s_mov_b32 s41, 0
	v_lshl_add_u64 v[88:89], v[86:87], 0, s[40:41]
	s_mov_b32 s40, 0xa01000
	v_lshl_add_u64 v[94:95], v[86:87], 0, s[40:41]
	global_load_dwordx4 v[160:163], v[88:89], off
	global_load_dwordx4 v[164:167], v[88:89], off offset:1024
	global_load_dwordx4 v[168:171], v[88:89], off offset:2048
	global_load_dwordx4 v[172:175], v[88:89], off offset:3072
	global_load_dwordx4 v[176:179], v[94:95], off
	global_load_dwordx4 v[180:183], v[94:95], off offset:1024
	global_load_dwordx4 v[184:187], v[94:95], off offset:2048
	global_load_dwordx4 v[188:191], v[94:95], off offset:3072
	s_mov_b32 s40, 0xb00000
	s_mov_b32 s41, 0
	v_lshl_add_u64 v[88:89], v[86:87], 0, s[40:41]
	s_mov_b32 s40, 0xb01000
	v_lshl_add_u64 v[94:95], v[86:87], 0, s[40:41]
	global_load_dwordx4 v[192:195], v[88:89], off
	global_load_dwordx4 v[196:199], v[88:89], off offset:1024
	global_load_dwordx4 v[200:203], v[88:89], off offset:2048
	global_load_dwordx4 v[204:207], v[88:89], off offset:3072
	global_load_dwordx4 v[208:211], v[94:95], off
	global_load_dwordx4 v[212:215], v[94:95], off offset:1024
	global_load_dwordx4 v[216:219], v[94:95], off offset:2048
	global_load_dwordx4 v[220:223], v[94:95], off offset:3072
	s_waitcnt vmcnt(31)
	v_pk_add_f32 v[82:83], v[82:83], v[96:97]
	v_pk_add_f32 v[80:81], v[80:81], v[98:99]
	s_waitcnt vmcnt(30)
	v_pk_add_f32 v[72:73], v[72:73], v[100:101]
	v_pk_add_f32 v[70:71], v[70:71], v[102:103]
	s_waitcnt vmcnt(29)
	v_pk_add_f32 v[84:85], v[84:85], v[104:105]
	v_pk_add_f32 v[20:21], v[20:21], v[106:107]
	s_waitcnt vmcnt(28)
	v_pk_add_f32 v[16:17], v[16:17], v[108:109]
	v_pk_add_f32 v[18:19], v[18:19], v[110:111]
	s_waitcnt vmcnt(27)
	v_pk_add_f32 v[12:13], v[12:13], v[112:113]
	v_pk_add_f32 v[14:15], v[14:15], v[114:115]
	s_waitcnt vmcnt(26)
	v_pk_add_f32 v[10:11], v[10:11], v[116:117]
	v_pk_add_f32 v[8:9], v[8:9], v[118:119]
	s_waitcnt vmcnt(25)
	v_pk_add_f32 v[0:1], v[0:1], v[120:121]
	v_pk_add_f32 v[2:3], v[2:3], v[122:123]
	s_waitcnt vmcnt(24)
	v_pk_add_f32 v[4:5], v[4:5], v[124:125]
	v_pk_add_f32 v[6:7], v[6:7], v[126:127]
	s_waitcnt vmcnt(23)
	v_pk_add_f32 v[82:83], v[82:83], v[128:129]
	v_pk_add_f32 v[80:81], v[80:81], v[130:131]
	s_waitcnt vmcnt(22)
	v_pk_add_f32 v[72:73], v[72:73], v[132:133]
	v_pk_add_f32 v[70:71], v[70:71], v[134:135]
	s_waitcnt vmcnt(21)
	v_pk_add_f32 v[84:85], v[84:85], v[136:137]
	v_pk_add_f32 v[20:21], v[20:21], v[138:139]
	s_waitcnt vmcnt(20)
	v_pk_add_f32 v[16:17], v[16:17], v[140:141]
	v_pk_add_f32 v[18:19], v[18:19], v[142:143]
	s_waitcnt vmcnt(19)
	v_pk_add_f32 v[12:13], v[12:13], v[144:145]
	v_pk_add_f32 v[14:15], v[14:15], v[146:147]
	s_waitcnt vmcnt(18)
	v_pk_add_f32 v[10:11], v[10:11], v[148:149]
	v_pk_add_f32 v[8:9], v[8:9], v[150:151]
	s_waitcnt vmcnt(17)
	v_pk_add_f32 v[0:1], v[0:1], v[152:153]
	v_pk_add_f32 v[2:3], v[2:3], v[154:155]
	s_waitcnt vmcnt(16)
	v_pk_add_f32 v[4:5], v[4:5], v[156:157]
	v_pk_add_f32 v[6:7], v[6:7], v[158:159]
	s_waitcnt vmcnt(15)
	v_pk_add_f32 v[82:83], v[82:83], v[160:161]
	v_pk_add_f32 v[80:81], v[80:81], v[162:163]
	s_waitcnt vmcnt(14)
	v_pk_add_f32 v[72:73], v[72:73], v[164:165]
	v_pk_add_f32 v[70:71], v[70:71], v[166:167]
	s_waitcnt vmcnt(13)
	v_pk_add_f32 v[84:85], v[84:85], v[168:169]
	v_pk_add_f32 v[20:21], v[20:21], v[170:171]
	s_waitcnt vmcnt(12)
	v_pk_add_f32 v[16:17], v[16:17], v[172:173]
	v_pk_add_f32 v[18:19], v[18:19], v[174:175]
	s_waitcnt vmcnt(11)
	v_pk_add_f32 v[12:13], v[12:13], v[176:177]
	v_pk_add_f32 v[14:15], v[14:15], v[178:179]
	s_waitcnt vmcnt(10)
	v_pk_add_f32 v[10:11], v[10:11], v[180:181]
	v_pk_add_f32 v[8:9], v[8:9], v[182:183]
	s_waitcnt vmcnt(9)
	v_pk_add_f32 v[0:1], v[0:1], v[184:185]
	v_pk_add_f32 v[2:3], v[2:3], v[186:187]
	s_waitcnt vmcnt(8)
	v_pk_add_f32 v[4:5], v[4:5], v[188:189]
	v_pk_add_f32 v[6:7], v[6:7], v[190:191]
	s_waitcnt vmcnt(7)
	v_pk_add_f32 v[82:83], v[82:83], v[192:193]
	v_pk_add_f32 v[80:81], v[80:81], v[194:195]
	s_waitcnt vmcnt(6)
	v_pk_add_f32 v[72:73], v[72:73], v[196:197]
	v_pk_add_f32 v[70:71], v[70:71], v[198:199]
	s_waitcnt vmcnt(5)
	v_pk_add_f32 v[84:85], v[84:85], v[200:201]
	v_pk_add_f32 v[20:21], v[20:21], v[202:203]
	s_waitcnt vmcnt(4)
	v_pk_add_f32 v[16:17], v[16:17], v[204:205]
	v_pk_add_f32 v[18:19], v[18:19], v[206:207]
	s_waitcnt vmcnt(3)
	v_pk_add_f32 v[12:13], v[12:13], v[208:209]
	v_pk_add_f32 v[14:15], v[14:15], v[210:211]
	s_waitcnt vmcnt(2)
	v_pk_add_f32 v[10:11], v[10:11], v[212:213]
	v_pk_add_f32 v[8:9], v[8:9], v[214:215]
	s_waitcnt vmcnt(1)
	v_pk_add_f32 v[0:1], v[0:1], v[216:217]
	v_pk_add_f32 v[2:3], v[2:3], v[218:219]
	s_waitcnt vmcnt(0)
	v_pk_add_f32 v[4:5], v[4:5], v[220:221]
	v_pk_add_f32 v[6:7], v[6:7], v[222:223]
	s_mov_b32 s40, 0xc00000
	s_mov_b32 s41, 0
	v_lshl_add_u64 v[88:89], v[86:87], 0, s[40:41]
	s_mov_b32 s40, 0xc01000
	v_lshl_add_u64 v[94:95], v[86:87], 0, s[40:41]
	global_load_dwordx4 v[96:99], v[88:89], off
	global_load_dwordx4 v[100:103], v[88:89], off offset:1024
	global_load_dwordx4 v[104:107], v[88:89], off offset:2048
	global_load_dwordx4 v[108:111], v[88:89], off offset:3072
	global_load_dwordx4 v[112:115], v[94:95], off
	global_load_dwordx4 v[116:119], v[94:95], off offset:1024
	global_load_dwordx4 v[120:123], v[94:95], off offset:2048
	global_load_dwordx4 v[124:127], v[94:95], off offset:3072
	s_mov_b32 s40, 0xd00000
	s_mov_b32 s41, 0
	v_lshl_add_u64 v[88:89], v[86:87], 0, s[40:41]
	s_mov_b32 s40, 0xd01000
	v_lshl_add_u64 v[94:95], v[86:87], 0, s[40:41]
	global_load_dwordx4 v[128:131], v[88:89], off
	global_load_dwordx4 v[132:135], v[88:89], off offset:1024
	global_load_dwordx4 v[136:139], v[88:89], off offset:2048
	global_load_dwordx4 v[140:143], v[88:89], off offset:3072
	global_load_dwordx4 v[144:147], v[94:95], off
	global_load_dwordx4 v[148:151], v[94:95], off offset:1024
	global_load_dwordx4 v[152:155], v[94:95], off offset:2048
	global_load_dwordx4 v[156:159], v[94:95], off offset:3072
	s_mov_b32 s40, 0xe00000
	s_mov_b32 s41, 0
	v_lshl_add_u64 v[88:89], v[86:87], 0, s[40:41]
	s_mov_b32 s40, 0xe01000
	v_lshl_add_u64 v[94:95], v[86:87], 0, s[40:41]
	global_load_dwordx4 v[160:163], v[88:89], off
	global_load_dwordx4 v[164:167], v[88:89], off offset:1024
	global_load_dwordx4 v[168:171], v[88:89], off offset:2048
	global_load_dwordx4 v[172:175], v[88:89], off offset:3072
	global_load_dwordx4 v[176:179], v[94:95], off
	global_load_dwordx4 v[180:183], v[94:95], off offset:1024
	global_load_dwordx4 v[184:187], v[94:95], off offset:2048
	global_load_dwordx4 v[188:191], v[94:95], off offset:3072
	s_mov_b32 s40, 0xf00000
	s_mov_b32 s41, 0
	v_lshl_add_u64 v[88:89], v[86:87], 0, s[40:41]
	s_mov_b32 s40, 0xf01000
	v_lshl_add_u64 v[94:95], v[86:87], 0, s[40:41]
	global_load_dwordx4 v[192:195], v[88:89], off
	global_load_dwordx4 v[196:199], v[88:89], off offset:1024
	global_load_dwordx4 v[200:203], v[88:89], off offset:2048
	global_load_dwordx4 v[204:207], v[88:89], off offset:3072
	global_load_dwordx4 v[208:211], v[94:95], off
	global_load_dwordx4 v[212:215], v[94:95], off offset:1024
	global_load_dwordx4 v[216:219], v[94:95], off offset:2048
	global_load_dwordx4 v[220:223], v[94:95], off offset:3072
	s_waitcnt vmcnt(31)
	v_pk_add_f32 v[82:83], v[82:83], v[96:97]
	v_pk_add_f32 v[80:81], v[80:81], v[98:99]
	s_waitcnt vmcnt(30)
	v_pk_add_f32 v[72:73], v[72:73], v[100:101]
	v_pk_add_f32 v[70:71], v[70:71], v[102:103]
	s_waitcnt vmcnt(29)
	v_pk_add_f32 v[84:85], v[84:85], v[104:105]
	v_pk_add_f32 v[20:21], v[20:21], v[106:107]
	s_waitcnt vmcnt(28)
	v_pk_add_f32 v[16:17], v[16:17], v[108:109]
	v_pk_add_f32 v[18:19], v[18:19], v[110:111]
	s_waitcnt vmcnt(27)
	v_pk_add_f32 v[12:13], v[12:13], v[112:113]
	v_pk_add_f32 v[14:15], v[14:15], v[114:115]
	s_waitcnt vmcnt(26)
	v_pk_add_f32 v[10:11], v[10:11], v[116:117]
	v_pk_add_f32 v[8:9], v[8:9], v[118:119]
	s_waitcnt vmcnt(25)
	v_pk_add_f32 v[0:1], v[0:1], v[120:121]
	v_pk_add_f32 v[2:3], v[2:3], v[122:123]
	s_waitcnt vmcnt(24)
	v_pk_add_f32 v[4:5], v[4:5], v[124:125]
	v_pk_add_f32 v[6:7], v[6:7], v[126:127]
	s_waitcnt vmcnt(23)
	v_pk_add_f32 v[82:83], v[82:83], v[128:129]
	v_pk_add_f32 v[80:81], v[80:81], v[130:131]
	s_waitcnt vmcnt(22)
	v_pk_add_f32 v[72:73], v[72:73], v[132:133]
	v_pk_add_f32 v[70:71], v[70:71], v[134:135]
	s_waitcnt vmcnt(21)
	v_pk_add_f32 v[84:85], v[84:85], v[136:137]
	v_pk_add_f32 v[20:21], v[20:21], v[138:139]
	s_waitcnt vmcnt(20)
	v_pk_add_f32 v[16:17], v[16:17], v[140:141]
	v_pk_add_f32 v[18:19], v[18:19], v[142:143]
	s_waitcnt vmcnt(19)
	v_pk_add_f32 v[12:13], v[12:13], v[144:145]
	v_pk_add_f32 v[14:15], v[14:15], v[146:147]
	s_waitcnt vmcnt(18)
	v_pk_add_f32 v[10:11], v[10:11], v[148:149]
	v_pk_add_f32 v[8:9], v[8:9], v[150:151]
	s_waitcnt vmcnt(17)
	v_pk_add_f32 v[0:1], v[0:1], v[152:153]
	v_pk_add_f32 v[2:3], v[2:3], v[154:155]
	s_waitcnt vmcnt(16)
	v_pk_add_f32 v[4:5], v[4:5], v[156:157]
	v_pk_add_f32 v[6:7], v[6:7], v[158:159]
	s_waitcnt vmcnt(15)
	v_pk_add_f32 v[82:83], v[82:83], v[160:161]
	v_pk_add_f32 v[80:81], v[80:81], v[162:163]
	s_waitcnt vmcnt(14)
	v_pk_add_f32 v[72:73], v[72:73], v[164:165]
	v_pk_add_f32 v[70:71], v[70:71], v[166:167]
	s_waitcnt vmcnt(13)
	v_pk_add_f32 v[84:85], v[84:85], v[168:169]
	v_pk_add_f32 v[20:21], v[20:21], v[170:171]
	s_waitcnt vmcnt(12)
	v_pk_add_f32 v[16:17], v[16:17], v[172:173]
	v_pk_add_f32 v[18:19], v[18:19], v[174:175]
	s_waitcnt vmcnt(11)
	v_pk_add_f32 v[12:13], v[12:13], v[176:177]
	v_pk_add_f32 v[14:15], v[14:15], v[178:179]
	s_waitcnt vmcnt(10)
	v_pk_add_f32 v[10:11], v[10:11], v[180:181]
	v_pk_add_f32 v[8:9], v[8:9], v[182:183]
	s_waitcnt vmcnt(9)
	v_pk_add_f32 v[0:1], v[0:1], v[184:185]
	v_pk_add_f32 v[2:3], v[2:3], v[186:187]
	s_waitcnt vmcnt(8)
	v_pk_add_f32 v[4:5], v[4:5], v[188:189]
	v_pk_add_f32 v[6:7], v[6:7], v[190:191]
	s_waitcnt vmcnt(7)
	v_pk_add_f32 v[82:83], v[82:83], v[192:193]
	v_pk_add_f32 v[80:81], v[80:81], v[194:195]
	s_waitcnt vmcnt(6)
	v_pk_add_f32 v[72:73], v[72:73], v[196:197]
	v_pk_add_f32 v[70:71], v[70:71], v[198:199]
	s_waitcnt vmcnt(5)
	v_pk_add_f32 v[84:85], v[84:85], v[200:201]
	v_pk_add_f32 v[20:21], v[20:21], v[202:203]
	s_waitcnt vmcnt(4)
	v_pk_add_f32 v[16:17], v[16:17], v[204:205]
	v_pk_add_f32 v[18:19], v[18:19], v[206:207]
	s_waitcnt vmcnt(3)
	v_pk_add_f32 v[12:13], v[12:13], v[208:209]
	v_pk_add_f32 v[14:15], v[14:15], v[210:211]
	s_waitcnt vmcnt(2)
	v_pk_add_f32 v[10:11], v[10:11], v[212:213]
	v_pk_add_f32 v[8:9], v[8:9], v[214:215]
	s_waitcnt vmcnt(1)
	v_pk_add_f32 v[0:1], v[0:1], v[216:217]
	v_pk_add_f32 v[2:3], v[2:3], v[218:219]
	s_waitcnt vmcnt(0)
	v_pk_add_f32 v[4:5], v[4:5], v[220:221]
	v_pk_add_f32 v[6:7], v[6:7], v[222:223]
	v_mov_b32_e32 v75, v8
	v_mov_b32_e32 v74, v11
	v_mov_b32_e32 v8, v10
	v_mov_b32_e32 v66, v15
	v_mov_b32_e32 v68, v13
	v_mov_b32_e32 v77, v20
	v_mov_b32_e32 v76, v85
	v_mov_b32_e32 v20, v84
	v_mov_b32_e32 v26, v71
	v_mov_b32_e32 v24, v73
	v_mov_b32_e32 v27, v81
	v_mov_b32_e32 v71, v80
	v_mov_b32_e32 v25, v83
	v_mov_b32_e32 v73, v82
